# P0 weight conversion rewritten by hand: wide loads, 3 tiles in flight per wave, no LDS; plus EpiRes/EpiUp epilogue load hoists
# speedup vs baseline: 1.0384x; 1.0321x over previous
.LBB0_24:
	v_writelane_b32 v253, s36, 42
	s_nop 1
	v_writelane_b32 v253, s37, 43
	v_writelane_b32 v253, s34, 44
	s_nop 1
	v_writelane_b32 v253, s35, 45
	s_or_b64 exec, exec, s[4:5]
	s_load_dwordx16 s[12:27], s[0:1], 0x0
	s_lshl_b32 s38, s78, 3
	s_waitcnt lgkmcnt(0)
	v_writelane_b32 v253, s12, 26
	s_nop 1
	v_writelane_b32 v253, s13, 27
	v_writelane_b32 v253, s14, 28
	v_writelane_b32 v253, s15, 29
	v_writelane_b32 v253, s16, 30
	v_writelane_b32 v253, s17, 31
	v_writelane_b32 v253, s18, 32
	v_writelane_b32 v253, s19, 33
	v_writelane_b32 v253, s20, 34
	v_writelane_b32 v253, s21, 35
	v_writelane_b32 v253, s22, 36
	v_writelane_b32 v253, s23, 37
	v_writelane_b32 v253, s24, 38
	v_writelane_b32 v253, s25, 39
	v_writelane_b32 v253, s26, 40
	v_writelane_b32 v253, s27, 41
	s_load_dwordx16 s[12:27], s[0:1], 0x40
	s_lshr_b32 s0, s8, 6
	s_lshl_b32 s1, s2, 3
	s_add_i32 s36, s0, s1
	s_waitcnt lgkmcnt(0)
	v_writelane_b32 v253, s12, 10
	s_nop 1
	v_writelane_b32 v253, s13, 11
	v_writelane_b32 v253, s14, 12
	v_writelane_b32 v253, s15, 13
	v_writelane_b32 v253, s16, 14
	v_writelane_b32 v253, s17, 15
	v_writelane_b32 v253, s18, 16
	v_writelane_b32 v253, s19, 17
	v_writelane_b32 v253, s20, 18
	v_writelane_b32 v253, s21, 19
	v_writelane_b32 v253, s22, 20
	v_writelane_b32 v253, s23, 21
	v_writelane_b32 v253, s24, 22
	v_writelane_b32 v253, s25, 23
	v_writelane_b32 v253, s26, 24
	v_writelane_b32 v253, s27, 25
	s_nop 0
	v_readlane_b32 s8, v253, 0
	v_readlane_b32 s10, v253, 2
	v_readlane_b32 s11, v253, 3
	s_add_u32 s64, s10, 0x400000
	s_addc_u32 s65, s11, 0
	s_cmpk_gt_i32 s36, 0x2fff
	v_readlane_b32 s9, v253, 1
	s_cbranch_scc1 .LBB0_178
	v_and_b32_e32 v219, 31, v227
	v_lshlrev_b32_e32 v212, 4, v219
	v_lshrrev_b32_e32 v213, 5, v227
	v_lshlrev_b32_e32 v214, 2, v219
	v_and_b32_e32 v215, 64, v214
	v_add_u32_e32 v215, v215, v214
	v_lshlrev_b32_e32 v216, 5, v213
	v_readlane_b32 s8, v253, 36
	v_readlane_b32 s9, v253, 37
	v_readlane_b32 s10, v253, 34
	v_readlane_b32 s11, v253, 35
	v_readlane_b32 s12, v253, 16
	v_readlane_b32 s13, v253, 17
	v_readlane_b32 s14, v253, 18
	v_readlane_b32 s15, v253, 19
	v_readlane_b32 s16, v253, 20
	v_readlane_b32 s17, v253, 21
	v_readlane_b32 s18, v253, 22
	v_readlane_b32 s19, v253, 23
	s_mov_b32 s66, s36
.Lwt_loop:
	s_cmpk_gt_i32 s66, 0x17ff
	s_cbranch_scc1 .Lwt_done
	s_lshl_b32 s67, s38, 1
	s_add_i32 s67, s67, s66
	s_cmpk_gt_i32 s67, 0x17ff
	s_cbranch_scc1 .Lwt_single
	s_cmpk_ge_i32 s66, 0xc00
	s_cselect_b32 s0, 1, 0
	s_mul_i32 s1, s0, 0xc00
	s_sub_i32 s1, s66, s1
	s_mul_i32 s4, s0, 0x1800000
	s_add_u32 s70, s64, s4
	s_addc_u32 s71, s65, 0
	s_lshl_b32 s69, s0, 12
	s_cmpk_lt_i32 s1, 0x300
	s_cbranch_scc1 .Lwt_in_1
	s_cmpk_lt_i32 s1, 0x400
	s_cbranch_scc1 .Lwt_out_1
	s_cmpk_lt_i32 s1, 0x800
	s_cbranch_scc1 .Lwt_up_1
	s_sub_i32 s1, s1, 0x800
	s_lshr_b32 s72, s1, 3
	s_and_b32 s73, s1, 7
	s_movk_i32 s74, 0x400
	s_mul_i32 s4, s0, 0x1000000
	s_add_u32 s76, s18, s4
	s_addc_u32 s77, s19, 0
	s_mov_b32 s4, 0x1000000
	s_lshl_b32 s5, s73, 7
	s_movk_i32 s27, 0xd00
	s_branch .Lwt_join_1
.Lwt_in_1:
	s_mul_i32 s72, s1, 0xaab
	s_lshr_b32 s72, s72, 16
	s_mul_i32 s73, s72, 24
	s_sub_i32 s73, s1, s73
	s_movk_i32 s74, 0xc00
	s_mul_i32 s4, s0, 0xc00000
	s_add_u32 s76, s8, s4
	s_addc_u32 s77, s9, 0
	s_add_u32 s24, s10, s69
	s_addc_u32 s25, s11, 0
	s_mov_b32 s4, 0
	s_movk_i32 s27, 0xb01
	s_cmpk_lt_u32 s73, 8
	s_cbranch_scc0 .Lwt_in_b_1
	s_and_b32 s5, s73, 3
	s_lshl_b32 s5, s5, 8
	s_lshr_b32 s75, s73, 2
	s_lshl_b32 s75, s75, 7
	s_add_i32 s5, s5, s75
	s_branch .Lwt_join_1
.Lwt_in_b_1:
	s_cmpk_lt_u32 s73, 16
	s_cbranch_scc0 .Lwt_in_c_1
	s_sub_i32 s75, s73, 8
	s_lshr_b32 s5, s75, 2
	s_lshl_b32 s5, s5, 9
	s_bfe_u32 s1, s75, 0x10001
	s_lshl_b32 s1, s1, 8
	s_add_i32 s5, s5, s1
	s_and_b32 s1, s75, 1
	s_lshl_b32 s1, s1, 6
	s_add_i32 s5, s5, s1
	s_addk_i32 s5, 0x400
	s_or_b32 s27, s27, 2
	s_branch .Lwt_join_1
.Lwt_in_c_1:
	s_lshl_b32 s5, s73, 7
	s_branch .Lwt_join_1
.Lwt_out_1:
	s_sub_i32 s1, s1, 0x300
	s_lshr_b32 s72, s1, 3
	s_and_b32 s73, s1, 7
	s_movk_i32 s74, 0x400
	s_mul_i32 s4, s0, 0x400000
	s_add_u32 s76, s12, s4
	s_addc_u32 s77, s13, 0
	s_mov_b32 s4, 0x600000
	s_lshl_b32 s5, s73, 7
	s_movk_i32 s27, 0xb00
	s_branch .Lwt_join_1
.Lwt_up_1:
	s_sub_i32 s1, s1, 0x400
	s_lshr_b32 s72, s1, 5
	s_and_b32 s73, s1, 31
	s_movk_i32 s74, 0x1000
	s_mul_i32 s4, s0, 0x1000000
	s_add_u32 s76, s16, s4
	s_addc_u32 s77, s17, 0
	s_add_u32 s24, s14, s69
	s_addc_u32 s25, s15, 0
	s_mov_b32 s4, 0x800000
	s_lshl_b32 s5, s73, 7
	s_movk_i32 s27, 0xb01
.Lwt_join_1:
	s_mul_i32 s0, s72, s74
	s_lshl_b32 s0, s0, 5
	s_lshl_b32 s1, s73, 7
	s_add_i32 s0, s0, s1
	s_lshl_b32 s0, s0, 2
	s_add_u32 s20, s76, s0
	s_addc_u32 s21, s77, 0
	s_lshl_b32 s26, s74, 2
	s_lshr_b32 s0, s27, 8
	s_lshl_b32 s0, s5, s0
	s_add_i32 s0, s0, s4
	s_lshl_b32 s1, s72, 6
	s_add_i32 s0, s0, s1
	s_add_u32 s22, s70, s0
	s_addc_u32 s23, s71, 0
	s_lshl_b32 s1, s72, 7
	s_add_u32 s24, s24, s1
	s_addc_u32 s25, s25, 0
	s_lshl_b32 s0, s26, 4
	v_mad_u32_u24 v217, v213, s0, v212
	global_load_dwordx4 v[4:7], v217, s[20:21] nt
	s_add_u32 s20, s20, s26
	s_addc_u32 s21, s21, 0
	global_load_dwordx4 v[8:11], v217, s[20:21] nt
	s_add_u32 s20, s20, s26
	s_addc_u32 s21, s21, 0
	global_load_dwordx4 v[12:15], v217, s[20:21] nt
	s_add_u32 s20, s20, s26
	s_addc_u32 s21, s21, 0
	global_load_dwordx4 v[16:19], v217, s[20:21] nt
	s_add_u32 s20, s20, s26
	s_addc_u32 s21, s21, 0
	global_load_dwordx4 v[20:23], v217, s[20:21] nt
	s_add_u32 s20, s20, s26
	s_addc_u32 s21, s21, 0
	global_load_dwordx4 v[24:27], v217, s[20:21] nt
	s_add_u32 s20, s20, s26
	s_addc_u32 s21, s21, 0
	global_load_dwordx4 v[28:31], v217, s[20:21] nt
	s_add_u32 s20, s20, s26
	s_addc_u32 s21, s21, 0
	global_load_dwordx4 v[32:35], v217, s[20:21] nt
	s_add_u32 s20, s20, s26
	s_addc_u32 s21, s21, 0
	global_load_dwordx4 v[36:39], v217, s[20:21] nt
	s_add_u32 s20, s20, s26
	s_addc_u32 s21, s21, 0
	global_load_dwordx4 v[40:43], v217, s[20:21] nt
	s_add_u32 s20, s20, s26
	s_addc_u32 s21, s21, 0
	global_load_dwordx4 v[44:47], v217, s[20:21] nt
	s_add_u32 s20, s20, s26
	s_addc_u32 s21, s21, 0
	global_load_dwordx4 v[48:51], v217, s[20:21] nt
	s_add_u32 s20, s20, s26
	s_addc_u32 s21, s21, 0
	global_load_dwordx4 v[52:55], v217, s[20:21] nt
	s_add_u32 s20, s20, s26
	s_addc_u32 s21, s21, 0
	global_load_dwordx4 v[56:59], v217, s[20:21] nt
	s_add_u32 s20, s20, s26
	s_addc_u32 s21, s21, 0
	global_load_dwordx4 v[60:63], v217, s[20:21] nt
	s_add_u32 s20, s20, s26
	s_addc_u32 s21, s21, 0
	global_load_dwordx4 v[64:67], v217, s[20:21] nt
	s_add_i32 s68, s66, s38
	s_cmpk_ge_i32 s68, 0xc00
	s_cselect_b32 s0, 1, 0
	s_mul_i32 s1, s0, 0xc00
	s_sub_i32 s1, s68, s1
	s_mul_i32 s4, s0, 0x1800000
	s_add_u32 s70, s64, s4
	s_addc_u32 s71, s65, 0
	s_lshl_b32 s69, s0, 12
	s_cmpk_lt_i32 s1, 0x300
	s_cbranch_scc1 .Lwt_in_2
	s_cmpk_lt_i32 s1, 0x400
	s_cbranch_scc1 .Lwt_out_2
	s_cmpk_lt_i32 s1, 0x800
	s_cbranch_scc1 .Lwt_up_2
	s_sub_i32 s1, s1, 0x800
	s_lshr_b32 s72, s1, 3
	s_and_b32 s73, s1, 7
	s_movk_i32 s74, 0x400
	s_mul_i32 s4, s0, 0x1000000
	s_add_u32 s76, s18, s4
	s_addc_u32 s77, s19, 0
	s_mov_b32 s4, 0x1000000
	s_lshl_b32 s5, s73, 7
	s_movk_i32 s35, 0xd00
	s_branch .Lwt_join_2
.Lwt_in_2:
	s_mul_i32 s72, s1, 0xaab
	s_lshr_b32 s72, s72, 16
	s_mul_i32 s73, s72, 24
	s_sub_i32 s73, s1, s73
	s_movk_i32 s74, 0xc00
	s_mul_i32 s4, s0, 0xc00000
	s_add_u32 s76, s8, s4
	s_addc_u32 s77, s9, 0
	s_add_u32 s32, s10, s69
	s_addc_u32 s33, s11, 0
	s_mov_b32 s4, 0
	s_movk_i32 s35, 0xb01
	s_cmpk_lt_u32 s73, 8
	s_cbranch_scc0 .Lwt_in_b_2
	s_and_b32 s5, s73, 3
	s_lshl_b32 s5, s5, 8
	s_lshr_b32 s75, s73, 2
	s_lshl_b32 s75, s75, 7
	s_add_i32 s5, s5, s75
	s_branch .Lwt_join_2
.Lwt_in_b_2:
	s_cmpk_lt_u32 s73, 16
	s_cbranch_scc0 .Lwt_in_c_2
	s_sub_i32 s75, s73, 8
	s_lshr_b32 s5, s75, 2
	s_lshl_b32 s5, s5, 9
	s_bfe_u32 s1, s75, 0x10001
	s_lshl_b32 s1, s1, 8
	s_add_i32 s5, s5, s1
	s_and_b32 s1, s75, 1
	s_lshl_b32 s1, s1, 6
	s_add_i32 s5, s5, s1
	s_addk_i32 s5, 0x400
	s_or_b32 s35, s35, 2
	s_branch .Lwt_join_2

.Lwt_out_2:
	s_sub_i32 s1, s1, 0x300
	s_lshr_b32 s72, s1, 3
	s_and_b32 s73, s1, 7
	s_movk_i32 s74, 0x400
	s_mul_i32 s4, s0, 0x400000
	s_add_u32 s76, s12, s4
	s_addc_u32 s77, s13, 0
	s_mov_b32 s4, 0x600000
	s_lshl_b32 s5, s73, 7
	s_movk_i32 s35, 0xb00
	s_branch .Lwt_join_2
.Lwt_up_2:
	s_sub_i32 s1, s1, 0x400
	s_lshr_b32 s72, s1, 5
	s_and_b32 s73, s1, 31
	s_movk_i32 s74, 0x1000
	s_mul_i32 s4, s0, 0x1000000
	s_add_u32 s76, s16, s4
	s_addc_u32 s77, s17, 0
	s_add_u32 s32, s14, s69
	s_addc_u32 s33, s15, 0
	s_mov_b32 s4, 0x800000
	s_lshl_b32 s5, s73, 7
	s_movk_i32 s35, 0xb01
.Lwt_join_2:
	s_mul_i32 s0, s72, s74
	s_lshl_b32 s0, s0, 5
	s_lshl_b32 s1, s73, 7
	s_add_i32 s0, s0, s1
	s_lshl_b32 s0, s0, 2
	s_add_u32 s28, s76, s0
	s_addc_u32 s29, s77, 0
	s_lshl_b32 s34, s74, 2
	s_lshr_b32 s0, s35, 8
	s_lshl_b32 s0, s5, s0
	s_add_i32 s0, s0, s4
	s_lshl_b32 s1, s72, 6
	s_add_i32 s0, s0, s1
	s_add_u32 s30, s70, s0
	s_addc_u32 s31, s71, 0
	s_lshl_b32 s1, s72, 7
	s_add_u32 s32, s32, s1
	s_addc_u32 s33, s33, 0
	s_lshl_b32 s0, s34, 4
	v_mad_u32_u24 v217, v213, s0, v212
	global_load_dwordx4 v[68:71], v217, s[28:29] nt
	s_add_u32 s28, s28, s34
	s_addc_u32 s29, s29, 0
	global_load_dwordx4 v[72:75], v217, s[28:29] nt
	s_add_u32 s28, s28, s34
	s_addc_u32 s29, s29, 0
	global_load_dwordx4 v[76:79], v217, s[28:29] nt
	s_add_u32 s28, s28, s34
	s_addc_u32 s29, s29, 0
	global_load_dwordx4 v[80:83], v217, s[28:29] nt
	s_add_u32 s28, s28, s34
	s_addc_u32 s29, s29, 0
	global_load_dwordx4 v[84:87], v217, s[28:29] nt
	s_add_u32 s28, s28, s34
	s_addc_u32 s29, s29, 0
	global_load_dwordx4 v[88:91], v217, s[28:29] nt
	s_add_u32 s28, s28, s34
	s_addc_u32 s29, s29, 0
	global_load_dwordx4 v[92:95], v217, s[28:29] nt
	s_add_u32 s28, s28, s34
	s_addc_u32 s29, s29, 0
	global_load_dwordx4 v[96:99], v217, s[28:29] nt
	s_add_u32 s28, s28, s34
	s_addc_u32 s29, s29, 0
	global_load_dwordx4 v[100:103], v217, s[28:29] nt
	s_add_u32 s28, s28, s34
	s_addc_u32 s29, s29, 0
	global_load_dwordx4 v[104:107], v217, s[28:29] nt
	s_add_u32 s28, s28, s34
	s_addc_u32 s29, s29, 0
	global_load_dwordx4 v[108:111], v217, s[28:29] nt
	s_add_u32 s28, s28, s34
	s_addc_u32 s29, s29, 0
	global_load_dwordx4 v[112:115], v217, s[28:29] nt
	s_add_u32 s28, s28, s34
	s_addc_u32 s29, s29, 0
	global_load_dwordx4 v[116:119], v217, s[28:29] nt
	s_add_u32 s28, s28, s34
	s_addc_u32 s29, s29, 0
	global_load_dwordx4 v[120:123], v217, s[28:29] nt
	s_add_u32 s28, s28, s34
	s_addc_u32 s29, s29, 0
	global_load_dwordx4 v[124:127], v217, s[28:29] nt
	s_add_u32 s28, s28, s34
	s_addc_u32 s29, s29, 0
	global_load_dwordx4 v[128:131], v217, s[28:29] nt
	s_cmpk_ge_i32 s67, 0xc00
	s_cselect_b32 s0, 1, 0
	s_mul_i32 s1, s0, 0xc00
	s_sub_i32 s1, s67, s1
	s_mul_i32 s4, s0, 0x1800000
	s_add_u32 s70, s64, s4
	s_addc_u32 s71, s65, 0
	s_lshl_b32 s69, s0, 12
	s_cmpk_lt_i32 s1, 0x300
	s_cbranch_scc1 .Lwt_in_3
	s_cmpk_lt_i32 s1, 0x400
	s_cbranch_scc1 .Lwt_out_3
	s_cmpk_lt_i32 s1, 0x800
	s_cbranch_scc1 .Lwt_up_3
	s_sub_i32 s1, s1, 0x800
	s_lshr_b32 s72, s1, 3
	s_and_b32 s73, s1, 7
	s_movk_i32 s74, 0x400
	s_mul_i32 s4, s0, 0x1000000
	s_add_u32 s76, s18, s4
	s_addc_u32 s77, s19, 0
	s_mov_b32 s4, 0x1000000
	s_lshl_b32 s5, s73, 7
	s_movk_i32 s47, 0xd00
	s_branch .Lwt_join_3
.Lwt_in_3:
	s_mul_i32 s72, s1, 0xaab
	s_lshr_b32 s72, s72, 16
	s_mul_i32 s73, s72, 24
	s_sub_i32 s73, s1, s73
	s_movk_i32 s74, 0xc00
	s_mul_i32 s4, s0, 0xc00000
	s_add_u32 s76, s8, s4
	s_addc_u32 s77, s9, 0
	s_add_u32 s44, s10, s69
	s_addc_u32 s45, s11, 0
	s_mov_b32 s4, 0
	s_movk_i32 s47, 0xb01
	s_cmpk_lt_u32 s73, 8
	s_cbranch_scc0 .Lwt_in_b_3
	s_and_b32 s5, s73, 3
	s_lshl_b32 s5, s5, 8
	s_lshr_b32 s75, s73, 2
	s_lshl_b32 s75, s75, 7
	s_add_i32 s5, s5, s75
	s_branch .Lwt_join_3
.Lwt_in_b_3:
	s_cmpk_lt_u32 s73, 16
	s_cbranch_scc0 .Lwt_in_c_3
	s_sub_i32 s75, s73, 8
	s_lshr_b32 s5, s75, 2
	s_lshl_b32 s5, s5, 9
	s_bfe_u32 s1, s75, 0x10001
	s_lshl_b32 s1, s1, 8
	s_add_i32 s5, s5, s1
	s_and_b32 s1, s75, 1
	s_lshl_b32 s1, s1, 6
	s_add_i32 s5, s5, s1
	s_addk_i32 s5, 0x400
	s_or_b32 s47, s47, 2
	s_branch .Lwt_join_3

.Lwt_out_3:
	s_sub_i32 s1, s1, 0x300
	s_lshr_b32 s72, s1, 3
	s_and_b32 s73, s1, 7
	s_movk_i32 s74, 0x400
	s_mul_i32 s4, s0, 0x400000
	s_add_u32 s76, s12, s4
	s_addc_u32 s77, s13, 0
	s_mov_b32 s4, 0x600000
	s_lshl_b32 s5, s73, 7
	s_movk_i32 s47, 0xb00
	s_branch .Lwt_join_3
.Lwt_up_3:
	s_sub_i32 s1, s1, 0x400
	s_lshr_b32 s72, s1, 5
	s_and_b32 s73, s1, 31
	s_movk_i32 s74, 0x1000
	s_mul_i32 s4, s0, 0x1000000
	s_add_u32 s76, s16, s4
	s_addc_u32 s77, s17, 0
	s_add_u32 s44, s14, s69
	s_addc_u32 s45, s15, 0
	s_mov_b32 s4, 0x800000
	s_lshl_b32 s5, s73, 7
	s_movk_i32 s47, 0xb01
.Lwt_join_3:
	s_mul_i32 s0, s72, s74
	s_lshl_b32 s0, s0, 5
	s_lshl_b32 s1, s73, 7
	s_add_i32 s0, s0, s1
	s_lshl_b32 s0, s0, 2
	s_add_u32 s40, s76, s0
	s_addc_u32 s41, s77, 0
	s_lshl_b32 s46, s74, 2
	s_lshr_b32 s0, s47, 8
	s_lshl_b32 s0, s5, s0
	s_add_i32 s0, s0, s4
	s_lshl_b32 s1, s72, 6
	s_add_i32 s0, s0, s1
	s_add_u32 s42, s70, s0
	s_addc_u32 s43, s71, 0
	s_lshl_b32 s1, s72, 7
	s_add_u32 s44, s44, s1
	s_addc_u32 s45, s45, 0
	s_lshl_b32 s0, s46, 4
	v_mad_u32_u24 v217, v213, s0, v212
	global_load_dwordx4 v[132:135], v217, s[40:41] nt
	s_add_u32 s40, s40, s46
	s_addc_u32 s41, s41, 0
	global_load_dwordx4 v[136:139], v217, s[40:41] nt
	s_add_u32 s40, s40, s46
	s_addc_u32 s41, s41, 0
	global_load_dwordx4 v[140:143], v217, s[40:41] nt
	s_add_u32 s40, s40, s46
	s_addc_u32 s41, s41, 0
	global_load_dwordx4 v[144:147], v217, s[40:41] nt
	s_add_u32 s40, s40, s46
	s_addc_u32 s41, s41, 0
	global_load_dwordx4 v[148:151], v217, s[40:41] nt
	s_add_u32 s40, s40, s46
	s_addc_u32 s41, s41, 0
	global_load_dwordx4 v[152:155], v217, s[40:41] nt
	s_add_u32 s40, s40, s46
	s_addc_u32 s41, s41, 0
	global_load_dwordx4 v[156:159], v217, s[40:41] nt
	s_add_u32 s40, s40, s46
	s_addc_u32 s41, s41, 0
	global_load_dwordx4 v[160:163], v217, s[40:41] nt
	s_add_u32 s40, s40, s46
	s_addc_u32 s41, s41, 0
	global_load_dwordx4 v[164:167], v217, s[40:41] nt
	s_add_u32 s40, s40, s46
	s_addc_u32 s41, s41, 0
	global_load_dwordx4 v[168:171], v217, s[40:41] nt
	s_add_u32 s40, s40, s46
	s_addc_u32 s41, s41, 0
	global_load_dwordx4 v[172:175], v217, s[40:41] nt
	s_add_u32 s40, s40, s46
	s_addc_u32 s41, s41, 0
	global_load_dwordx4 v[176:179], v217, s[40:41] nt
	s_add_u32 s40, s40, s46
	s_addc_u32 s41, s41, 0
	global_load_dwordx4 v[180:183], v217, s[40:41] nt
	s_add_u32 s40, s40, s46
	s_addc_u32 s41, s41, 0
	global_load_dwordx4 v[184:187], v217, s[40:41] nt
	s_add_u32 s40, s40, s46
	s_addc_u32 s41, s41, 0
	global_load_dwordx4 v[188:191], v217, s[40:41] nt
	s_add_u32 s40, s40, s46
	s_addc_u32 s41, s41, 0
	global_load_dwordx4 v[192:195], v217, s[40:41] nt
	s_bitcmp1_b32 s27, 0
	s_cbranch_scc0 .Lwt_nog_4
	s_load_dwordx16 s[80:95], s[24:25], 0x0
	s_load_dwordx16 s[48:63], s[24:25], 0x40
.Lwt_nog_4:
	s_bitcmp1_b32 s27, 1
	s_cselect_b64 vcc, -1, 0
	s_lshr_b32 s0, s27, 8
	s_lshl_b32 s4, 1, s0
	v_cndmask_b32_e32 v219, v214, v215, vcc
	v_lshlrev_b32_e32 v218, s0, v219
	v_add_u32_e32 v218, v218, v216
	s_waitcnt vmcnt(32)
	s_bitcmp1_b32 s27, 0
	s_cbranch_scc0 .Lwt_nomul_4
	s_waitcnt lgkmcnt(0)
	s_mov_b32 exec_hi, 0
	v_mul_f32_e32 v4, s80, v4
	v_mul_f32_e32 v5, s80, v5
	v_mul_f32_e32 v6, s80, v6
	v_mul_f32_e32 v7, s80, v7
	v_mul_f32_e32 v8, s81, v8
	v_mul_f32_e32 v9, s81, v9
	v_mul_f32_e32 v10, s81, v10
	v_mul_f32_e32 v11, s81, v11
	v_mul_f32_e32 v12, s82, v12
	v_mul_f32_e32 v13, s82, v13
	v_mul_f32_e32 v14, s82, v14
	v_mul_f32_e32 v15, s82, v15
	v_mul_f32_e32 v16, s83, v16
	v_mul_f32_e32 v17, s83, v17
	v_mul_f32_e32 v18, s83, v18
	v_mul_f32_e32 v19, s83, v19
	v_mul_f32_e32 v20, s84, v20
	v_mul_f32_e32 v21, s84, v21
	v_mul_f32_e32 v22, s84, v22
	v_mul_f32_e32 v23, s84, v23
	v_mul_f32_e32 v24, s85, v24
	v_mul_f32_e32 v25, s85, v25
	v_mul_f32_e32 v26, s85, v26
	v_mul_f32_e32 v27, s85, v27
	v_mul_f32_e32 v28, s86, v28
	v_mul_f32_e32 v29, s86, v29
	v_mul_f32_e32 v30, s86, v30
	v_mul_f32_e32 v31, s86, v31
	v_mul_f32_e32 v32, s87, v32
	v_mul_f32_e32 v33, s87, v33
	v_mul_f32_e32 v34, s87, v34
	v_mul_f32_e32 v35, s87, v35
	v_mul_f32_e32 v36, s88, v36
	v_mul_f32_e32 v37, s88, v37
	v_mul_f32_e32 v38, s88, v38
	v_mul_f32_e32 v39, s88, v39
	v_mul_f32_e32 v40, s89, v40
	v_mul_f32_e32 v41, s89, v41
	v_mul_f32_e32 v42, s89, v42
	v_mul_f32_e32 v43, s89, v43
	v_mul_f32_e32 v44, s90, v44
	v_mul_f32_e32 v45, s90, v45
	v_mul_f32_e32 v46, s90, v46
	v_mul_f32_e32 v47, s90, v47
	v_mul_f32_e32 v48, s91, v48
	v_mul_f32_e32 v49, s91, v49
	v_mul_f32_e32 v50, s91, v50
	v_mul_f32_e32 v51, s91, v51
	v_mul_f32_e32 v52, s92, v52
	v_mul_f32_e32 v53, s92, v53
	v_mul_f32_e32 v54, s92, v54
	v_mul_f32_e32 v55, s92, v55
	v_mul_f32_e32 v56, s93, v56
	v_mul_f32_e32 v57, s93, v57
	v_mul_f32_e32 v58, s93, v58
	v_mul_f32_e32 v59, s93, v59
	v_mul_f32_e32 v60, s94, v60
	v_mul_f32_e32 v61, s94, v61
	v_mul_f32_e32 v62, s94, v62
	v_mul_f32_e32 v63, s94, v63
	v_mul_f32_e32 v64, s95, v64
	v_mul_f32_e32 v65, s95, v65
	v_mul_f32_e32 v66, s95, v66
	v_mul_f32_e32 v67, s95, v67
	s_mov_b32 exec_lo, 0
	s_mov_b32 exec_hi, -1
	v_mul_f32_e32 v4, s48, v4
	v_mul_f32_e32 v5, s48, v5
	v_mul_f32_e32 v6, s48, v6
	v_mul_f32_e32 v7, s48, v7
	v_mul_f32_e32 v8, s49, v8
	v_mul_f32_e32 v9, s49, v9
	v_mul_f32_e32 v10, s49, v10
	v_mul_f32_e32 v11, s49, v11
	v_mul_f32_e32 v12, s50, v12
	v_mul_f32_e32 v13, s50, v13
	v_mul_f32_e32 v14, s50, v14
	v_mul_f32_e32 v15, s50, v15
	v_mul_f32_e32 v16, s51, v16
	v_mul_f32_e32 v17, s51, v17
	v_mul_f32_e32 v18, s51, v18
	v_mul_f32_e32 v19, s51, v19
	v_mul_f32_e32 v20, s52, v20
	v_mul_f32_e32 v21, s52, v21
	v_mul_f32_e32 v22, s52, v22
	v_mul_f32_e32 v23, s52, v23
	v_mul_f32_e32 v24, s53, v24
	v_mul_f32_e32 v25, s53, v25
	v_mul_f32_e32 v26, s53, v26
	v_mul_f32_e32 v27, s53, v27
	v_mul_f32_e32 v28, s54, v28
	v_mul_f32_e32 v29, s54, v29
	v_mul_f32_e32 v30, s54, v30
	v_mul_f32_e32 v31, s54, v31
	v_mul_f32_e32 v32, s55, v32
	v_mul_f32_e32 v33, s55, v33
	v_mul_f32_e32 v34, s55, v34
	v_mul_f32_e32 v35, s55, v35
	v_mul_f32_e32 v36, s56, v36
	v_mul_f32_e32 v37, s56, v37
	v_mul_f32_e32 v38, s56, v38
	v_mul_f32_e32 v39, s56, v39
	v_mul_f32_e32 v40, s57, v40
	v_mul_f32_e32 v41, s57, v41
	v_mul_f32_e32 v42, s57, v42
	v_mul_f32_e32 v43, s57, v43
	v_mul_f32_e32 v44, s58, v44
	v_mul_f32_e32 v45, s58, v45
	v_mul_f32_e32 v46, s58, v46
	v_mul_f32_e32 v47, s58, v47
	v_mul_f32_e32 v48, s59, v48
	v_mul_f32_e32 v49, s59, v49
	v_mul_f32_e32 v50, s59, v50
	v_mul_f32_e32 v51, s59, v51
	v_mul_f32_e32 v52, s60, v52
	v_mul_f32_e32 v53, s60, v53
	v_mul_f32_e32 v54, s60, v54
	v_mul_f32_e32 v55, s60, v55
	v_mul_f32_e32 v56, s61, v56
	v_mul_f32_e32 v57, s61, v57
	v_mul_f32_e32 v58, s61, v58
	v_mul_f32_e32 v59, s61, v59
	v_mul_f32_e32 v60, s62, v60
	v_mul_f32_e32 v61, s62, v61
	v_mul_f32_e32 v62, s62, v62
	v_mul_f32_e32 v63, s62, v63
	v_mul_f32_e32 v64, s63, v64
	v_mul_f32_e32 v65, s63, v65
	v_mul_f32_e32 v66, s63, v66
	v_mul_f32_e32 v67, s63, v67
	s_mov_b64 exec, -1
.Lwt_nomul_4:
	v_cvt_pk_bf16_f32 v196, v4, v8
	v_cvt_pk_bf16_f32 v197, v12, v16
	v_cvt_pk_bf16_f32 v198, v20, v24
	v_cvt_pk_bf16_f32 v199, v28, v32
	global_store_dwordx4 v218, v[196:199], s[22:23]
	v_cvt_pk_bf16_f32 v200, v36, v40
	v_cvt_pk_bf16_f32 v201, v44, v48
	v_cvt_pk_bf16_f32 v202, v52, v56
	v_cvt_pk_bf16_f32 v203, v60, v64
	global_store_dwordx4 v218, v[200:203], s[22:23] offset:16
	s_add_u32 s22, s22, s4
	s_addc_u32 s23, s23, 0
	v_cvt_pk_bf16_f32 v204, v5, v9
	v_cvt_pk_bf16_f32 v205, v13, v17
	v_cvt_pk_bf16_f32 v206, v21, v25
	v_cvt_pk_bf16_f32 v207, v29, v33
	global_store_dwordx4 v218, v[204:207], s[22:23]
	v_cvt_pk_bf16_f32 v208, v37, v41
	v_cvt_pk_bf16_f32 v209, v45, v49
	v_cvt_pk_bf16_f32 v210, v53, v57
	v_cvt_pk_bf16_f32 v211, v61, v65
	global_store_dwordx4 v218, v[208:211], s[22:23] offset:16
	s_add_u32 s22, s22, s4
	s_addc_u32 s23, s23, 0
	v_cvt_pk_bf16_f32 v196, v6, v10
	v_cvt_pk_bf16_f32 v197, v14, v18
	v_cvt_pk_bf16_f32 v198, v22, v26
	v_cvt_pk_bf16_f32 v199, v30, v34
	global_store_dwordx4 v218, v[196:199], s[22:23]
	v_cvt_pk_bf16_f32 v200, v38, v42
	v_cvt_pk_bf16_f32 v201, v46, v50
	v_cvt_pk_bf16_f32 v202, v54, v58
	v_cvt_pk_bf16_f32 v203, v62, v66
	global_store_dwordx4 v218, v[200:203], s[22:23] offset:16
	s_add_u32 s22, s22, s4
	s_addc_u32 s23, s23, 0
	v_cvt_pk_bf16_f32 v204, v7, v11
	v_cvt_pk_bf16_f32 v205, v15, v19
	v_cvt_pk_bf16_f32 v206, v23, v27
	v_cvt_pk_bf16_f32 v207, v31, v35
	global_store_dwordx4 v218, v[204:207], s[22:23]
	v_cvt_pk_bf16_f32 v208, v39, v43
	v_cvt_pk_bf16_f32 v209, v47, v51
	v_cvt_pk_bf16_f32 v210, v55, v59
	v_cvt_pk_bf16_f32 v211, v63, v67
	global_store_dwordx4 v218, v[208:211], s[22:23] offset:16
	s_bitcmp1_b32 s35, 0
	s_cbranch_scc0 .Lwt_nog_5
	s_load_dwordx16 s[80:95], s[32:33], 0x0
	s_load_dwordx16 s[48:63], s[32:33], 0x40
.Lwt_nog_5:
	s_bitcmp1_b32 s35, 1
	s_cselect_b64 vcc, -1, 0
	s_lshr_b32 s0, s35, 8
	s_lshl_b32 s4, 1, s0
	v_cndmask_b32_e32 v219, v214, v215, vcc
	v_lshlrev_b32_e32 v218, s0, v219
	v_add_u32_e32 v218, v218, v216
	s_waitcnt vmcnt(24)
	s_bitcmp1_b32 s35, 0
	s_cbranch_scc0 .Lwt_nomul_5
	s_waitcnt lgkmcnt(0)
	s_mov_b32 exec_hi, 0
	v_mul_f32_e32 v68, s80, v68
	v_mul_f32_e32 v69, s80, v69
	v_mul_f32_e32 v70, s80, v70
	v_mul_f32_e32 v71, s80, v71
	v_mul_f32_e32 v72, s81, v72
	v_mul_f32_e32 v73, s81, v73
	v_mul_f32_e32 v74, s81, v74
	v_mul_f32_e32 v75, s81, v75
	v_mul_f32_e32 v76, s82, v76
	v_mul_f32_e32 v77, s82, v77
	v_mul_f32_e32 v78, s82, v78
	v_mul_f32_e32 v79, s82, v79
	v_mul_f32_e32 v80, s83, v80
	v_mul_f32_e32 v81, s83, v81
	v_mul_f32_e32 v82, s83, v82
	v_mul_f32_e32 v83, s83, v83
	v_mul_f32_e32 v84, s84, v84
	v_mul_f32_e32 v85, s84, v85
	v_mul_f32_e32 v86, s84, v86
	v_mul_f32_e32 v87, s84, v87
	v_mul_f32_e32 v88, s85, v88
	v_mul_f32_e32 v89, s85, v89
	v_mul_f32_e32 v90, s85, v90
	v_mul_f32_e32 v91, s85, v91
	v_mul_f32_e32 v92, s86, v92
	v_mul_f32_e32 v93, s86, v93
	v_mul_f32_e32 v94, s86, v94
	v_mul_f32_e32 v95, s86, v95
	v_mul_f32_e32 v96, s87, v96
	v_mul_f32_e32 v97, s87, v97
	v_mul_f32_e32 v98, s87, v98
	v_mul_f32_e32 v99, s87, v99
	v_mul_f32_e32 v100, s88, v100
	v_mul_f32_e32 v101, s88, v101
	v_mul_f32_e32 v102, s88, v102
	v_mul_f32_e32 v103, s88, v103
	v_mul_f32_e32 v104, s89, v104
	v_mul_f32_e32 v105, s89, v105
	v_mul_f32_e32 v106, s89, v106
	v_mul_f32_e32 v107, s89, v107
	v_mul_f32_e32 v108, s90, v108
	v_mul_f32_e32 v109, s90, v109
	v_mul_f32_e32 v110, s90, v110
	v_mul_f32_e32 v111, s90, v111
	v_mul_f32_e32 v112, s91, v112
	v_mul_f32_e32 v113, s91, v113
	v_mul_f32_e32 v114, s91, v114
	v_mul_f32_e32 v115, s91, v115
	v_mul_f32_e32 v116, s92, v116
	v_mul_f32_e32 v117, s92, v117
	v_mul_f32_e32 v118, s92, v118
	v_mul_f32_e32 v119, s92, v119
	v_mul_f32_e32 v120, s93, v120
	v_mul_f32_e32 v121, s93, v121
	v_mul_f32_e32 v122, s93, v122
	v_mul_f32_e32 v123, s93, v123
	v_mul_f32_e32 v124, s94, v124
	v_mul_f32_e32 v125, s94, v125
	v_mul_f32_e32 v126, s94, v126
	v_mul_f32_e32 v127, s94, v127
	v_mul_f32_e32 v128, s95, v128
	v_mul_f32_e32 v129, s95, v129
	v_mul_f32_e32 v130, s95, v130
	v_mul_f32_e32 v131, s95, v131
	s_mov_b32 exec_lo, 0
	s_mov_b32 exec_hi, -1
	v_mul_f32_e32 v68, s48, v68
	v_mul_f32_e32 v69, s48, v69
	v_mul_f32_e32 v70, s48, v70
	v_mul_f32_e32 v71, s48, v71
	v_mul_f32_e32 v72, s49, v72
	v_mul_f32_e32 v73, s49, v73
	v_mul_f32_e32 v74, s49, v74
	v_mul_f32_e32 v75, s49, v75
	v_mul_f32_e32 v76, s50, v76
	v_mul_f32_e32 v77, s50, v77
	v_mul_f32_e32 v78, s50, v78
	v_mul_f32_e32 v79, s50, v79
	v_mul_f32_e32 v80, s51, v80
	v_mul_f32_e32 v81, s51, v81
	v_mul_f32_e32 v82, s51, v82
	v_mul_f32_e32 v83, s51, v83
	v_mul_f32_e32 v84, s52, v84
	v_mul_f32_e32 v85, s52, v85
	v_mul_f32_e32 v86, s52, v86
	v_mul_f32_e32 v87, s52, v87
	v_mul_f32_e32 v88, s53, v88
	v_mul_f32_e32 v89, s53, v89
	v_mul_f32_e32 v90, s53, v90
	v_mul_f32_e32 v91, s53, v91
	v_mul_f32_e32 v92, s54, v92
	v_mul_f32_e32 v93, s54, v93
	v_mul_f32_e32 v94, s54, v94
	v_mul_f32_e32 v95, s54, v95
	v_mul_f32_e32 v96, s55, v96
	v_mul_f32_e32 v97, s55, v97
	v_mul_f32_e32 v98, s55, v98
	v_mul_f32_e32 v99, s55, v99
	v_mul_f32_e32 v100, s56, v100
	v_mul_f32_e32 v101, s56, v101
	v_mul_f32_e32 v102, s56, v102
	v_mul_f32_e32 v103, s56, v103
	v_mul_f32_e32 v104, s57, v104
	v_mul_f32_e32 v105, s57, v105
	v_mul_f32_e32 v106, s57, v106
	v_mul_f32_e32 v107, s57, v107
	v_mul_f32_e32 v108, s58, v108
	v_mul_f32_e32 v109, s58, v109
	v_mul_f32_e32 v110, s58, v110
	v_mul_f32_e32 v111, s58, v111
	v_mul_f32_e32 v112, s59, v112
	v_mul_f32_e32 v113, s59, v113
	v_mul_f32_e32 v114, s59, v114
	v_mul_f32_e32 v115, s59, v115
	v_mul_f32_e32 v116, s60, v116
	v_mul_f32_e32 v117, s60, v117
	v_mul_f32_e32 v118, s60, v118
	v_mul_f32_e32 v119, s60, v119
	v_mul_f32_e32 v120, s61, v120
	v_mul_f32_e32 v121, s61, v121
	v_mul_f32_e32 v122, s61, v122
	v_mul_f32_e32 v123, s61, v123
	v_mul_f32_e32 v124, s62, v124
	v_mul_f32_e32 v125, s62, v125
	v_mul_f32_e32 v126, s62, v126
	v_mul_f32_e32 v127, s62, v127
	v_mul_f32_e32 v128, s63, v128
	v_mul_f32_e32 v129, s63, v129
	v_mul_f32_e32 v130, s63, v130
	v_mul_f32_e32 v131, s63, v131
	s_mov_b64 exec, -1
.Lwt_nomul_5:
	v_cvt_pk_bf16_f32 v196, v68, v72
	v_cvt_pk_bf16_f32 v197, v76, v80
	v_cvt_pk_bf16_f32 v198, v84, v88
	v_cvt_pk_bf16_f32 v199, v92, v96
	global_store_dwordx4 v218, v[196:199], s[30:31]
	v_cvt_pk_bf16_f32 v200, v100, v104
	v_cvt_pk_bf16_f32 v201, v108, v112
	v_cvt_pk_bf16_f32 v202, v116, v120
	v_cvt_pk_bf16_f32 v203, v124, v128
	global_store_dwordx4 v218, v[200:203], s[30:31] offset:16
	s_add_u32 s30, s30, s4
	s_addc_u32 s31, s31, 0
	v_cvt_pk_bf16_f32 v204, v69, v73
	v_cvt_pk_bf16_f32 v205, v77, v81
	v_cvt_pk_bf16_f32 v206, v85, v89
	v_cvt_pk_bf16_f32 v207, v93, v97
	global_store_dwordx4 v218, v[204:207], s[30:31]
	v_cvt_pk_bf16_f32 v208, v101, v105
	v_cvt_pk_bf16_f32 v209, v109, v113
	v_cvt_pk_bf16_f32 v210, v117, v121
	v_cvt_pk_bf16_f32 v211, v125, v129
	global_store_dwordx4 v218, v[208:211], s[30:31] offset:16
	s_add_u32 s30, s30, s4
	s_addc_u32 s31, s31, 0
	v_cvt_pk_bf16_f32 v196, v70, v74
	v_cvt_pk_bf16_f32 v197, v78, v82
	v_cvt_pk_bf16_f32 v198, v86, v90
	v_cvt_pk_bf16_f32 v199, v94, v98
	global_store_dwordx4 v218, v[196:199], s[30:31]
	v_cvt_pk_bf16_f32 v200, v102, v106
	v_cvt_pk_bf16_f32 v201, v110, v114
	v_cvt_pk_bf16_f32 v202, v118, v122
	v_cvt_pk_bf16_f32 v203, v126, v130
	global_store_dwordx4 v218, v[200:203], s[30:31] offset:16
	s_add_u32 s30, s30, s4
	s_addc_u32 s31, s31, 0
	v_cvt_pk_bf16_f32 v204, v71, v75
	v_cvt_pk_bf16_f32 v205, v79, v83
	v_cvt_pk_bf16_f32 v206, v87, v91
	v_cvt_pk_bf16_f32 v207, v95, v99
	global_store_dwordx4 v218, v[204:207], s[30:31]
	v_cvt_pk_bf16_f32 v208, v103, v107
	v_cvt_pk_bf16_f32 v209, v111, v115
	v_cvt_pk_bf16_f32 v210, v119, v123
	v_cvt_pk_bf16_f32 v211, v127, v131
	global_store_dwordx4 v218, v[208:211], s[30:31] offset:16
	s_bitcmp1_b32 s47, 0
	s_cbranch_scc0 .Lwt_nog_6
	s_load_dwordx16 s[80:95], s[44:45], 0x0
	s_load_dwordx16 s[48:63], s[44:45], 0x40
.Lwt_nog_6:
	s_bitcmp1_b32 s47, 1
	s_cselect_b64 vcc, -1, 0
	s_lshr_b32 s0, s47, 8
	s_lshl_b32 s4, 1, s0
	v_cndmask_b32_e32 v219, v214, v215, vcc
	v_lshlrev_b32_e32 v218, s0, v219
	v_add_u32_e32 v218, v218, v216
	s_waitcnt vmcnt(16)
	s_bitcmp1_b32 s47, 0
	s_cbranch_scc0 .Lwt_nomul_6
	s_waitcnt lgkmcnt(0)
	s_mov_b32 exec_hi, 0
	v_mul_f32_e32 v132, s80, v132
	v_mul_f32_e32 v133, s80, v133
	v_mul_f32_e32 v134, s80, v134
	v_mul_f32_e32 v135, s80, v135
	v_mul_f32_e32 v136, s81, v136
	v_mul_f32_e32 v137, s81, v137
	v_mul_f32_e32 v138, s81, v138
	v_mul_f32_e32 v139, s81, v139
	v_mul_f32_e32 v140, s82, v140
	v_mul_f32_e32 v141, s82, v141
	v_mul_f32_e32 v142, s82, v142
	v_mul_f32_e32 v143, s82, v143
	v_mul_f32_e32 v144, s83, v144
	v_mul_f32_e32 v145, s83, v145
	v_mul_f32_e32 v146, s83, v146
	v_mul_f32_e32 v147, s83, v147
	v_mul_f32_e32 v148, s84, v148
	v_mul_f32_e32 v149, s84, v149
	v_mul_f32_e32 v150, s84, v150
	v_mul_f32_e32 v151, s84, v151
	v_mul_f32_e32 v152, s85, v152
	v_mul_f32_e32 v153, s85, v153
	v_mul_f32_e32 v154, s85, v154
	v_mul_f32_e32 v155, s85, v155
	v_mul_f32_e32 v156, s86, v156
	v_mul_f32_e32 v157, s86, v157
	v_mul_f32_e32 v158, s86, v158
	v_mul_f32_e32 v159, s86, v159
	v_mul_f32_e32 v160, s87, v160
	v_mul_f32_e32 v161, s87, v161
	v_mul_f32_e32 v162, s87, v162
	v_mul_f32_e32 v163, s87, v163
	v_mul_f32_e32 v164, s88, v164
	v_mul_f32_e32 v165, s88, v165
	v_mul_f32_e32 v166, s88, v166
	v_mul_f32_e32 v167, s88, v167
	v_mul_f32_e32 v168, s89, v168
	v_mul_f32_e32 v169, s89, v169
	v_mul_f32_e32 v170, s89, v170
	v_mul_f32_e32 v171, s89, v171
	v_mul_f32_e32 v172, s90, v172
	v_mul_f32_e32 v173, s90, v173
	v_mul_f32_e32 v174, s90, v174
	v_mul_f32_e32 v175, s90, v175
	v_mul_f32_e32 v176, s91, v176
	v_mul_f32_e32 v177, s91, v177
	v_mul_f32_e32 v178, s91, v178
	v_mul_f32_e32 v179, s91, v179
	v_mul_f32_e32 v180, s92, v180
	v_mul_f32_e32 v181, s92, v181
	v_mul_f32_e32 v182, s92, v182
	v_mul_f32_e32 v183, s92, v183
	v_mul_f32_e32 v184, s93, v184
	v_mul_f32_e32 v185, s93, v185
	v_mul_f32_e32 v186, s93, v186
	v_mul_f32_e32 v187, s93, v187
	v_mul_f32_e32 v188, s94, v188
	v_mul_f32_e32 v189, s94, v189
	v_mul_f32_e32 v190, s94, v190
	v_mul_f32_e32 v191, s94, v191
	v_mul_f32_e32 v192, s95, v192
	v_mul_f32_e32 v193, s95, v193
	v_mul_f32_e32 v194, s95, v194
	v_mul_f32_e32 v195, s95, v195
	s_mov_b32 exec_lo, 0
	s_mov_b32 exec_hi, -1
	v_mul_f32_e32 v132, s48, v132
	v_mul_f32_e32 v133, s48, v133
	v_mul_f32_e32 v134, s48, v134
	v_mul_f32_e32 v135, s48, v135
	v_mul_f32_e32 v136, s49, v136
	v_mul_f32_e32 v137, s49, v137
	v_mul_f32_e32 v138, s49, v138
	v_mul_f32_e32 v139, s49, v139
	v_mul_f32_e32 v140, s50, v140
	v_mul_f32_e32 v141, s50, v141
	v_mul_f32_e32 v142, s50, v142
	v_mul_f32_e32 v143, s50, v143
	v_mul_f32_e32 v144, s51, v144
	v_mul_f32_e32 v145, s51, v145
	v_mul_f32_e32 v146, s51, v146
	v_mul_f32_e32 v147, s51, v147
	v_mul_f32_e32 v148, s52, v148
	v_mul_f32_e32 v149, s52, v149
	v_mul_f32_e32 v150, s52, v150
	v_mul_f32_e32 v151, s52, v151
	v_mul_f32_e32 v152, s53, v152
	v_mul_f32_e32 v153, s53, v153
	v_mul_f32_e32 v154, s53, v154
	v_mul_f32_e32 v155, s53, v155
	v_mul_f32_e32 v156, s54, v156
	v_mul_f32_e32 v157, s54, v157
	v_mul_f32_e32 v158, s54, v158
	v_mul_f32_e32 v159, s54, v159
	v_mul_f32_e32 v160, s55, v160
	v_mul_f32_e32 v161, s55, v161
	v_mul_f32_e32 v162, s55, v162
	v_mul_f32_e32 v163, s55, v163
	v_mul_f32_e32 v164, s56, v164
	v_mul_f32_e32 v165, s56, v165
	v_mul_f32_e32 v166, s56, v166
	v_mul_f32_e32 v167, s56, v167
	v_mul_f32_e32 v168, s57, v168
	v_mul_f32_e32 v169, s57, v169
	v_mul_f32_e32 v170, s57, v170
	v_mul_f32_e32 v171, s57, v171
	v_mul_f32_e32 v172, s58, v172
	v_mul_f32_e32 v173, s58, v173
	v_mul_f32_e32 v174, s58, v174
	v_mul_f32_e32 v175, s58, v175
	v_mul_f32_e32 v176, s59, v176
	v_mul_f32_e32 v177, s59, v177
	v_mul_f32_e32 v178, s59, v178
	v_mul_f32_e32 v179, s59, v179
	v_mul_f32_e32 v180, s60, v180
	v_mul_f32_e32 v181, s60, v181
	v_mul_f32_e32 v182, s60, v182
	v_mul_f32_e32 v183, s60, v183
	v_mul_f32_e32 v184, s61, v184
	v_mul_f32_e32 v185, s61, v185
	v_mul_f32_e32 v186, s61, v186
	v_mul_f32_e32 v187, s61, v187
	v_mul_f32_e32 v188, s62, v188
	v_mul_f32_e32 v189, s62, v189
	v_mul_f32_e32 v190, s62, v190
	v_mul_f32_e32 v191, s62, v191
	v_mul_f32_e32 v192, s63, v192
	v_mul_f32_e32 v193, s63, v193
	v_mul_f32_e32 v194, s63, v194
	v_mul_f32_e32 v195, s63, v195
	s_mov_b64 exec, -1
.Lwt_nomul_6:
	v_cvt_pk_bf16_f32 v196, v132, v136
	v_cvt_pk_bf16_f32 v197, v140, v144
	v_cvt_pk_bf16_f32 v198, v148, v152
	v_cvt_pk_bf16_f32 v199, v156, v160
	global_store_dwordx4 v218, v[196:199], s[42:43]
	v_cvt_pk_bf16_f32 v200, v164, v168
	v_cvt_pk_bf16_f32 v201, v172, v176
	v_cvt_pk_bf16_f32 v202, v180, v184
	v_cvt_pk_bf16_f32 v203, v188, v192
	global_store_dwordx4 v218, v[200:203], s[42:43] offset:16
	s_add_u32 s42, s42, s4
	s_addc_u32 s43, s43, 0
	v_cvt_pk_bf16_f32 v204, v133, v137
	v_cvt_pk_bf16_f32 v205, v141, v145
	v_cvt_pk_bf16_f32 v206, v149, v153
	v_cvt_pk_bf16_f32 v207, v157, v161
	global_store_dwordx4 v218, v[204:207], s[42:43]
	v_cvt_pk_bf16_f32 v208, v165, v169
	v_cvt_pk_bf16_f32 v209, v173, v177
	v_cvt_pk_bf16_f32 v210, v181, v185
	v_cvt_pk_bf16_f32 v211, v189, v193
	global_store_dwordx4 v218, v[208:211], s[42:43] offset:16
	s_add_u32 s42, s42, s4
	s_addc_u32 s43, s43, 0
	v_cvt_pk_bf16_f32 v196, v134, v138
	v_cvt_pk_bf16_f32 v197, v142, v146
	v_cvt_pk_bf16_f32 v198, v150, v154
	v_cvt_pk_bf16_f32 v199, v158, v162
	global_store_dwordx4 v218, v[196:199], s[42:43]
	v_cvt_pk_bf16_f32 v200, v166, v170
	v_cvt_pk_bf16_f32 v201, v174, v178
	v_cvt_pk_bf16_f32 v202, v182, v186
	v_cvt_pk_bf16_f32 v203, v190, v194
	global_store_dwordx4 v218, v[200:203], s[42:43] offset:16
	s_add_u32 s42, s42, s4
	s_addc_u32 s43, s43, 0
	v_cvt_pk_bf16_f32 v204, v135, v139
	v_cvt_pk_bf16_f32 v205, v143, v147
	v_cvt_pk_bf16_f32 v206, v151, v155
	v_cvt_pk_bf16_f32 v207, v159, v163
	global_store_dwordx4 v218, v[204:207], s[42:43]
	v_cvt_pk_bf16_f32 v208, v167, v171
	v_cvt_pk_bf16_f32 v209, v175, v179
	v_cvt_pk_bf16_f32 v210, v183, v187
	v_cvt_pk_bf16_f32 v211, v191, v195
	global_store_dwordx4 v218, v[208:211], s[42:43] offset:16
	s_add_i32 s66, s67, s38
	s_branch .Lwt_loop
.Lwt_single:
	s_cmpk_ge_i32 s66, 0xc00
	s_cselect_b32 s0, 1, 0
	s_mul_i32 s1, s0, 0xc00
	s_sub_i32 s1, s66, s1
	s_mul_i32 s4, s0, 0x1800000
	s_add_u32 s70, s64, s4
	s_addc_u32 s71, s65, 0
	s_lshl_b32 s69, s0, 12
	s_cmpk_lt_i32 s1, 0x300
	s_cbranch_scc1 .Lwt_in_7
	s_cmpk_lt_i32 s1, 0x400
	s_cbranch_scc1 .Lwt_out_7
	s_cmpk_lt_i32 s1, 0x800
	s_cbranch_scc1 .Lwt_up_7
	s_sub_i32 s1, s1, 0x800
	s_lshr_b32 s72, s1, 3
	s_and_b32 s73, s1, 7
	s_movk_i32 s74, 0x400
	s_mul_i32 s4, s0, 0x1000000
	s_add_u32 s76, s18, s4
	s_addc_u32 s77, s19, 0
	s_mov_b32 s4, 0x1000000
	s_lshl_b32 s5, s73, 7
	s_movk_i32 s27, 0xd00
	s_branch .Lwt_join_7

.Lwt_join_7:
	s_mul_i32 s0, s72, s74
	s_lshl_b32 s0, s0, 5
	s_lshl_b32 s1, s73, 7
	s_add_i32 s0, s0, s1
	s_lshl_b32 s0, s0, 2
	s_add_u32 s20, s76, s0
	s_addc_u32 s21, s77, 0
	s_lshl_b32 s26, s74, 2
	s_lshr_b32 s0, s27, 8
	s_lshl_b32 s0, s5, s0
	s_add_i32 s0, s0, s4
	s_lshl_b32 s1, s72, 6
	s_add_i32 s0, s0, s1
	s_add_u32 s22, s70, s0
	s_addc_u32 s23, s71, 0
	s_lshl_b32 s1, s72, 7
	s_add_u32 s24, s24, s1
	s_addc_u32 s25, s25, 0
	s_lshl_b32 s0, s26, 4
	v_mad_u32_u24 v217, v213, s0, v212
	global_load_dwordx4 v[4:7], v217, s[20:21] nt
	s_add_u32 s20, s20, s26
	s_addc_u32 s21, s21, 0
	global_load_dwordx4 v[8:11], v217, s[20:21] nt
	s_add_u32 s20, s20, s26
	s_addc_u32 s21, s21, 0
	global_load_dwordx4 v[12:15], v217, s[20:21] nt
	s_add_u32 s20, s20, s26
	s_addc_u32 s21, s21, 0
	global_load_dwordx4 v[16:19], v217, s[20:21] nt
	s_add_u32 s20, s20, s26
	s_addc_u32 s21, s21, 0
	global_load_dwordx4 v[20:23], v217, s[20:21] nt
	s_add_u32 s20, s20, s26
	s_addc_u32 s21, s21, 0
	global_load_dwordx4 v[24:27], v217, s[20:21] nt
	s_add_u32 s20, s20, s26
	s_addc_u32 s21, s21, 0
	global_load_dwordx4 v[28:31], v217, s[20:21] nt
	s_add_u32 s20, s20, s26
	s_addc_u32 s21, s21, 0
	global_load_dwordx4 v[32:35], v217, s[20:21] nt
	s_add_u32 s20, s20, s26
	s_addc_u32 s21, s21, 0
	global_load_dwordx4 v[36:39], v217, s[20:21] nt
	s_add_u32 s20, s20, s26
	s_addc_u32 s21, s21, 0
	global_load_dwordx4 v[40:43], v217, s[20:21] nt
	s_add_u32 s20, s20, s26
	s_addc_u32 s21, s21, 0
	global_load_dwordx4 v[44:47], v217, s[20:21] nt
	s_add_u32 s20, s20, s26
	s_addc_u32 s21, s21, 0
	global_load_dwordx4 v[48:51], v217, s[20:21] nt
	s_add_u32 s20, s20, s26
	s_addc_u32 s21, s21, 0
	global_load_dwordx4 v[52:55], v217, s[20:21] nt
	s_add_u32 s20, s20, s26
	s_addc_u32 s21, s21, 0
	global_load_dwordx4 v[56:59], v217, s[20:21] nt
	s_add_u32 s20, s20, s26
	s_addc_u32 s21, s21, 0
	global_load_dwordx4 v[60:63], v217, s[20:21] nt
	s_add_u32 s20, s20, s26
	s_addc_u32 s21, s21, 0
	global_load_dwordx4 v[64:67], v217, s[20:21] nt
	s_bitcmp1_b32 s27, 0
	s_cbranch_scc0 .Lwt_nog_8
	s_load_dwordx16 s[80:95], s[24:25], 0x0
	s_load_dwordx16 s[48:63], s[24:25], 0x40
.Lwt_nog_8:
	s_bitcmp1_b32 s27, 1
	s_cselect_b64 vcc, -1, 0
	s_lshr_b32 s0, s27, 8
	s_lshl_b32 s4, 1, s0
	v_cndmask_b32_e32 v219, v214, v215, vcc
	v_lshlrev_b32_e32 v218, s0, v219
	v_add_u32_e32 v218, v218, v216
	s_waitcnt vmcnt(0)
	s_bitcmp1_b32 s27, 0
	s_cbranch_scc0 .Lwt_nomul_8
	s_waitcnt lgkmcnt(0)
	s_mov_b32 exec_hi, 0
	v_mul_f32_e32 v4, s80, v4
	v_mul_f32_e32 v5, s80, v5
	v_mul_f32_e32 v6, s80, v6
	v_mul_f32_e32 v7, s80, v7
	v_mul_f32_e32 v8, s81, v8
	v_mul_f32_e32 v9, s81, v9
	v_mul_f32_e32 v10, s81, v10
	v_mul_f32_e32 v11, s81, v11
	v_mul_f32_e32 v12, s82, v12
	v_mul_f32_e32 v13, s82, v13
	v_mul_f32_e32 v14, s82, v14
	v_mul_f32_e32 v15, s82, v15
	v_mul_f32_e32 v16, s83, v16
	v_mul_f32_e32 v17, s83, v17
	v_mul_f32_e32 v18, s83, v18
	v_mul_f32_e32 v19, s83, v19
	v_mul_f32_e32 v20, s84, v20
	v_mul_f32_e32 v21, s84, v21
	v_mul_f32_e32 v22, s84, v22
	v_mul_f32_e32 v23, s84, v23
	v_mul_f32_e32 v24, s85, v24
	v_mul_f32_e32 v25, s85, v25
	v_mul_f32_e32 v26, s85, v26
	v_mul_f32_e32 v27, s85, v27
	v_mul_f32_e32 v28, s86, v28
	v_mul_f32_e32 v29, s86, v29
	v_mul_f32_e32 v30, s86, v30
	v_mul_f32_e32 v31, s86, v31
	v_mul_f32_e32 v32, s87, v32
	v_mul_f32_e32 v33, s87, v33
	v_mul_f32_e32 v34, s87, v34
	v_mul_f32_e32 v35, s87, v35
	v_mul_f32_e32 v36, s88, v36
	v_mul_f32_e32 v37, s88, v37
	v_mul_f32_e32 v38, s88, v38
	v_mul_f32_e32 v39, s88, v39
	v_mul_f32_e32 v40, s89, v40
	v_mul_f32_e32 v41, s89, v41
	v_mul_f32_e32 v42, s89, v42
	v_mul_f32_e32 v43, s89, v43
	v_mul_f32_e32 v44, s90, v44
	v_mul_f32_e32 v45, s90, v45
	v_mul_f32_e32 v46, s90, v46
	v_mul_f32_e32 v47, s90, v47
	v_mul_f32_e32 v48, s91, v48
	v_mul_f32_e32 v49, s91, v49
	v_mul_f32_e32 v50, s91, v50
	v_mul_f32_e32 v51, s91, v51
	v_mul_f32_e32 v52, s92, v52
	v_mul_f32_e32 v53, s92, v53
	v_mul_f32_e32 v54, s92, v54
	v_mul_f32_e32 v55, s92, v55
	v_mul_f32_e32 v56, s93, v56
	v_mul_f32_e32 v57, s93, v57
	v_mul_f32_e32 v58, s93, v58
	v_mul_f32_e32 v59, s93, v59
	v_mul_f32_e32 v60, s94, v60
	v_mul_f32_e32 v61, s94, v61
	v_mul_f32_e32 v62, s94, v62
	v_mul_f32_e32 v63, s94, v63
	v_mul_f32_e32 v64, s95, v64
	v_mul_f32_e32 v65, s95, v65
	v_mul_f32_e32 v66, s95, v66
	v_mul_f32_e32 v67, s95, v67
	s_mov_b32 exec_lo, 0
	s_mov_b32 exec_hi, -1
	v_mul_f32_e32 v4, s48, v4
	v_mul_f32_e32 v5, s48, v5
	v_mul_f32_e32 v6, s48, v6
	v_mul_f32_e32 v7, s48, v7
	v_mul_f32_e32 v8, s49, v8
	v_mul_f32_e32 v9, s49, v9
	v_mul_f32_e32 v10, s49, v10
	v_mul_f32_e32 v11, s49, v11
	v_mul_f32_e32 v12, s50, v12
	v_mul_f32_e32 v13, s50, v13
	v_mul_f32_e32 v14, s50, v14
	v_mul_f32_e32 v15, s50, v15
	v_mul_f32_e32 v16, s51, v16
	v_mul_f32_e32 v17, s51, v17
	v_mul_f32_e32 v18, s51, v18
	v_mul_f32_e32 v19, s51, v19
	v_mul_f32_e32 v20, s52, v20
	v_mul_f32_e32 v21, s52, v21
	v_mul_f32_e32 v22, s52, v22
	v_mul_f32_e32 v23, s52, v23
	v_mul_f32_e32 v24, s53, v24
	v_mul_f32_e32 v25, s53, v25
	v_mul_f32_e32 v26, s53, v26
	v_mul_f32_e32 v27, s53, v27
	v_mul_f32_e32 v28, s54, v28
	v_mul_f32_e32 v29, s54, v29
	v_mul_f32_e32 v30, s54, v30
	v_mul_f32_e32 v31, s54, v31
	v_mul_f32_e32 v32, s55, v32
	v_mul_f32_e32 v33, s55, v33
	v_mul_f32_e32 v34, s55, v34
	v_mul_f32_e32 v35, s55, v35
	v_mul_f32_e32 v36, s56, v36
	v_mul_f32_e32 v37, s56, v37
	v_mul_f32_e32 v38, s56, v38
	v_mul_f32_e32 v39, s56, v39
	v_mul_f32_e32 v40, s57, v40
	v_mul_f32_e32 v41, s57, v41
	v_mul_f32_e32 v42, s57, v42
	v_mul_f32_e32 v43, s57, v43
	v_mul_f32_e32 v44, s58, v44
	v_mul_f32_e32 v45, s58, v45
	v_mul_f32_e32 v46, s58, v46
	v_mul_f32_e32 v47, s58, v47
	v_mul_f32_e32 v48, s59, v48
	v_mul_f32_e32 v49, s59, v49
	v_mul_f32_e32 v50, s59, v50
	v_mul_f32_e32 v51, s59, v51
	v_mul_f32_e32 v52, s60, v52
	v_mul_f32_e32 v53, s60, v53
	v_mul_f32_e32 v54, s60, v54
	v_mul_f32_e32 v55, s60, v55
	v_mul_f32_e32 v56, s61, v56
	v_mul_f32_e32 v57, s61, v57
	v_mul_f32_e32 v58, s61, v58
	v_mul_f32_e32 v59, s61, v59
	v_mul_f32_e32 v60, s62, v60
	v_mul_f32_e32 v61, s62, v61
	v_mul_f32_e32 v62, s62, v62
	v_mul_f32_e32 v63, s62, v63
	v_mul_f32_e32 v64, s63, v64
	v_mul_f32_e32 v65, s63, v65
	v_mul_f32_e32 v66, s63, v66
	v_mul_f32_e32 v67, s63, v67
	s_mov_b64 exec, -1
.Lwt_nomul_8:
	v_cvt_pk_bf16_f32 v196, v4, v8
	v_cvt_pk_bf16_f32 v197, v12, v16
	v_cvt_pk_bf16_f32 v198, v20, v24
	v_cvt_pk_bf16_f32 v199, v28, v32
	global_store_dwordx4 v218, v[196:199], s[22:23]
	v_cvt_pk_bf16_f32 v200, v36, v40
	v_cvt_pk_bf16_f32 v201, v44, v48
	v_cvt_pk_bf16_f32 v202, v52, v56
	v_cvt_pk_bf16_f32 v203, v60, v64
	global_store_dwordx4 v218, v[200:203], s[22:23] offset:16
	s_add_u32 s22, s22, s4
	s_addc_u32 s23, s23, 0
	v_cvt_pk_bf16_f32 v204, v5, v9
	v_cvt_pk_bf16_f32 v205, v13, v17
	v_cvt_pk_bf16_f32 v206, v21, v25
	v_cvt_pk_bf16_f32 v207, v29, v33
	global_store_dwordx4 v218, v[204:207], s[22:23]
	v_cvt_pk_bf16_f32 v208, v37, v41
	v_cvt_pk_bf16_f32 v209, v45, v49
	v_cvt_pk_bf16_f32 v210, v53, v57
	v_cvt_pk_bf16_f32 v211, v61, v65
	global_store_dwordx4 v218, v[208:211], s[22:23] offset:16
	s_add_u32 s22, s22, s4
	s_addc_u32 s23, s23, 0
	v_cvt_pk_bf16_f32 v196, v6, v10
	v_cvt_pk_bf16_f32 v197, v14, v18
	v_cvt_pk_bf16_f32 v198, v22, v26
	v_cvt_pk_bf16_f32 v199, v30, v34
	global_store_dwordx4 v218, v[196:199], s[22:23]
	v_cvt_pk_bf16_f32 v200, v38, v42
	v_cvt_pk_bf16_f32 v201, v46, v50
	v_cvt_pk_bf16_f32 v202, v54, v58
	v_cvt_pk_bf16_f32 v203, v62, v66
	global_store_dwordx4 v218, v[200:203], s[22:23] offset:16
	s_add_u32 s22, s22, s4
	s_addc_u32 s23, s23, 0
	v_cvt_pk_bf16_f32 v204, v7, v11
	v_cvt_pk_bf16_f32 v205, v15, v19
	v_cvt_pk_bf16_f32 v206, v23, v27
	v_cvt_pk_bf16_f32 v207, v31, v35
	global_store_dwordx4 v218, v[204:207], s[22:23]
	v_cvt_pk_bf16_f32 v208, v39, v43
	v_cvt_pk_bf16_f32 v209, v47, v51
	v_cvt_pk_bf16_f32 v210, v55, v59
	v_cvt_pk_bf16_f32 v211, v63, v67
	global_store_dwordx4 v218, v[208:211], s[22:23] offset:16
	s_add_i32 s66, s66, s38
	s_branch .Lwt_loop
.Lwt_done:
.LBB0_178:
	v_readlane_b32 s8, v253, 0
	v_readlane_b32 s10, v253, 2
	v_readlane_b32 s11, v253, 3
	s_add_u32 s46, s10, 0x3400000
	s_addc_u32 s47, s11, 0
	s_cmpk_lt_i32 s36, 0x4200
	s_cselect_b64 s[0:1], -1, 0
	v_readlane_b32 s9, v253, 1
	v_writelane_b32 v253, s0, 46
	s_cmpk_gt_i32 s36, 0x41ff
	v_mbcnt_lo_u32_b32 v42, -1, 0
	v_writelane_b32 v253, s1, 47
	s_cbranch_scc1 .LBB0_192
	v_mbcnt_hi_u32_b32 v3, -1, v42
	v_and_b32_e32 v1, 64, v3
	v_add_u32_e32 v4, 64, v1
	v_xor_b32_e32 v1, 1, v3
	v_cmp_lt_i32_e32 vcc, v1, v4
	v_xor_b32_e32 v5, 2, v3
	v_mov_b32_e32 v35, 0
	v_cndmask_b32_e32 v1, v3, v1, vcc
	v_cmp_lt_i32_e32 vcc, v5, v4
	v_lshlrev_b32_e32 v34, 3, v227
	v_lshl_add_u64 v[36:37], s[46:47], 0, v[34:35]
	v_cndmask_b32_e32 v5, v3, v5, vcc
	v_lshlrev_b32_e32 v34, 2, v5
	v_xor_b32_e32 v5, 4, v3
	v_cmp_lt_i32_e32 vcc, v5, v4
	s_ashr_i32 s39, s38, 31
	v_cmp_eq_u32_e64 s[0:1], 0, v227
	v_cndmask_b32_e32 v5, v3, v5, vcc
	v_lshlrev_b32_e32 v43, 2, v5
	v_xor_b32_e32 v5, 8, v3
	v_cmp_lt_i32_e32 vcc, v5, v4
	v_lshlrev_b32_e32 v1, 2, v1
	v_lshlrev_b32_e32 v47, 2, v2
	v_cndmask_b32_e32 v5, v3, v5, vcc
	v_lshlrev_b32_e32 v44, 2, v5
	v_xor_b32_e32 v5, 16, v3
	v_cmp_lt_i32_e32 vcc, v5, v4
	s_lshl_b64 s[10:11], s[38:39], 2
	s_mov_b32 s14, s36
	v_cndmask_b32_e32 v5, v3, v5, vcc
	v_lshlrev_b32_e32 v45, 2, v5
	v_xor_b32_e32 v5, 32, v3
	v_cmp_lt_i32_e32 vcc, v5, v4
	s_nop 1
	v_cndmask_b32_e32 v3, v3, v5, vcc
	v_lshlrev_b32_e32 v46, 2, v3
	s_branch .LBB0_181
